# sample GEMM epilogue stores write-through (sc1), 16-WG sub-barrier without L2 write-back, on top of combined build
# baseline (speedup 1.0000x reference)
.LBB0_213:
	v_lshl_add_u32 v128, s4, 8, v141
	v_ashrrev_i32_e32 v129, 31, v128
	v_lshl_add_u64 v[130:131], v[128:129], 2, s[88:89]
	global_load_dword v136, v[130:131], off
	global_load_dword v236, v[130:131], off offset:64
	global_load_dword v237, v[130:131], off offset:128
	global_load_dword v238, v[130:131], off offset:192
	global_load_dword v239, v[130:131], off offset:512
	global_load_dword v240, v[130:131], off offset:576
	global_load_dword v241, v[130:131], off offset:640
	global_load_dword v242, v[130:131], off offset:704
	v_ashrrev_i32_e32 v129, 1, v140
	s_lshl_b32 s1, s0, 8
	v_readlane_b32 s4, v235, 37
	v_and_b32_e32 v129, -8, v129
	s_or_b32 s1, s4, s1
	v_add_u32_e32 v134, s1, v129
	s_movk_i32 s0, 0x1040
	v_mov_b64_e32 v[132:133], s[52:53]
	v_ashrrev_i32_e32 v135, 31, v134
	v_mad_i64_i32 v[138:139], s[4:5], v128, s0, v[132:133]
	v_or_b32_e32 v140, 16, v128
	v_lshlrev_b64 v[134:135], 1, v[134:135]
	v_ashrrev_i32_e32 v141, 31, v140
	v_lshl_add_u64 v[138:139], v[138:139], 0, v[134:135]
	v_lshl_add_u64 v[142:143], v[140:141], 2, s[88:89]
	s_movk_i32 s1, 0x80
	v_writelane_b32 v235, s1, 45
	s_waitcnt vmcnt(0)
	v_pk_mul_f32 v[126:127], v[126:127], v[136:137] op_sel_hi:[1,0]
	v_pk_mul_f32 v[124:125], v[124:125], v[136:137] op_sel_hi:[1,0]
	v_pk_mul_f32 v[122:123], v[122:123], v[136:137] op_sel_hi:[1,0]
	v_pk_mul_f32 v[120:121], v[120:121], v[136:137] op_sel_hi:[1,0]
	v_pk_mul_f32 v[118:119], v[118:119], v[136:137] op_sel_hi:[1,0]
	v_pk_mul_f32 v[116:117], v[116:117], v[136:137] op_sel_hi:[1,0]
	v_pk_mul_f32 v[144:145], v[114:115], v[136:137] op_sel_hi:[1,0]
	v_pk_mul_f32 v[136:137], v[112:113], v[136:137] op_sel_hi:[1,0]
	v_cvt_pk_bf16_f32 v112, v124, v125
	v_cvt_pk_bf16_f32 v113, v126, v127
	v_cvt_pk_bf16_f32 v114, v120, v121
	v_cvt_pk_bf16_f32 v115, v122, v123
	global_store_dwordx4 v[138:139], v[112:115], off sc1
	s_nop 1
	v_cvt_pk_bf16_f32 v112, v116, v117
	v_cvt_pk_bf16_f32 v113, v118, v119
	v_cvt_pk_bf16_f32 v114, v136, v137
	v_cvt_pk_bf16_f32 v115, v144, v145
	global_store_dwordx4 v[138:139], v[112:115], off offset:256 sc1
	s_nop 1
	v_mad_i64_i32 v[116:117], s[4:5], v140, s0, v[132:133]
	v_or_b32_e32 v114, 32, v128
	v_ashrrev_i32_e32 v115, 31, v114
	v_lshl_add_u64 v[116:117], v[116:117], 0, v[134:135]
	v_lshl_add_u64 v[118:119], v[114:115], 2, s[88:89]
	s_nop 1
	v_mov_b32_e32 v112, v236
	v_pk_mul_f32 v[110:111], v[110:111], v[112:113] op_sel_hi:[1,0]
	v_pk_mul_f32 v[108:109], v[108:109], v[112:113] op_sel_hi:[1,0]
	v_pk_mul_f32 v[106:107], v[106:107], v[112:113] op_sel_hi:[1,0]
	v_pk_mul_f32 v[104:105], v[104:105], v[112:113] op_sel_hi:[1,0]
	v_pk_mul_f32 v[102:103], v[102:103], v[112:113] op_sel_hi:[1,0]
	v_pk_mul_f32 v[100:101], v[100:101], v[112:113] op_sel_hi:[1,0]
	v_pk_mul_f32 v[120:121], v[98:99], v[112:113] op_sel_hi:[1,0]
	v_pk_mul_f32 v[112:113], v[96:97], v[112:113] op_sel_hi:[1,0]
	v_cvt_pk_bf16_f32 v96, v108, v109
	v_cvt_pk_bf16_f32 v97, v110, v111
	v_cvt_pk_bf16_f32 v98, v104, v105
	v_cvt_pk_bf16_f32 v99, v106, v107
	global_store_dwordx4 v[116:117], v[96:99], off sc1
	s_nop 1
	v_cvt_pk_bf16_f32 v96, v100, v101
	v_cvt_pk_bf16_f32 v97, v102, v103
	v_cvt_pk_bf16_f32 v98, v112, v113
	v_cvt_pk_bf16_f32 v99, v120, v121
	global_store_dwordx4 v[116:117], v[96:99], off offset:256 sc1
	s_nop 1
	v_mad_i64_i32 v[100:101], s[4:5], v114, s0, v[132:133]
	v_or_b32_e32 v98, 48, v128
	v_ashrrev_i32_e32 v99, 31, v98
	v_lshl_add_u64 v[100:101], v[100:101], 0, v[134:135]
	v_lshl_add_u64 v[102:103], v[98:99], 2, s[88:89]
	s_nop 1
	v_mov_b32_e32 v96, v237
	v_pk_mul_f32 v[94:95], v[94:95], v[96:97] op_sel_hi:[1,0]
	v_pk_mul_f32 v[92:93], v[92:93], v[96:97] op_sel_hi:[1,0]
	v_pk_mul_f32 v[90:91], v[90:91], v[96:97] op_sel_hi:[1,0]
	v_pk_mul_f32 v[88:89], v[88:89], v[96:97] op_sel_hi:[1,0]
	v_pk_mul_f32 v[82:83], v[82:83], v[96:97] op_sel_hi:[1,0]
	v_pk_mul_f32 v[80:81], v[80:81], v[96:97] op_sel_hi:[1,0]
	v_pk_mul_f32 v[104:105], v[74:75], v[96:97] op_sel_hi:[1,0]
	v_pk_mul_f32 v[96:97], v[72:73], v[96:97] op_sel_hi:[1,0]
	v_cvt_pk_bf16_f32 v72, v92, v93
	v_cvt_pk_bf16_f32 v73, v94, v95
	v_cvt_pk_bf16_f32 v74, v88, v89
	v_cvt_pk_bf16_f32 v75, v90, v91
	global_store_dwordx4 v[100:101], v[72:75], off sc1
	s_nop 1
	v_cvt_pk_bf16_f32 v72, v80, v81
	v_cvt_pk_bf16_f32 v73, v82, v83
	v_cvt_pk_bf16_f32 v74, v96, v97
	v_cvt_pk_bf16_f32 v75, v104, v105
	global_store_dwordx4 v[100:101], v[72:75], off offset:256 sc1
	s_nop 1
	s_nop 1
	v_mov_b32_e32 v72, v238
	v_pk_mul_f32 v[80:81], v[86:87], v[72:73] op_sel_hi:[1,0]
	v_mad_i64_i32 v[74:75], s[4:5], v98, s0, v[132:133]
	v_lshl_add_u64 v[74:75], v[74:75], 0, v[134:135]
	v_pk_mul_f32 v[82:83], v[84:85], v[72:73] op_sel_hi:[1,0]
	v_pk_mul_f32 v[78:79], v[78:79], v[72:73] op_sel_hi:[1,0]
	v_pk_mul_f32 v[76:77], v[76:77], v[72:73] op_sel_hi:[1,0]
	v_pk_mul_f32 v[70:71], v[70:71], v[72:73] op_sel_hi:[1,0]
	v_pk_mul_f32 v[68:69], v[68:69], v[72:73] op_sel_hi:[1,0]
	v_pk_mul_f32 v[84:85], v[66:67], v[72:73] op_sel_hi:[1,0]
	v_pk_mul_f32 v[72:73], v[64:65], v[72:73] op_sel_hi:[1,0]
	v_cvt_pk_bf16_f32 v64, v82, v83
	v_cvt_pk_bf16_f32 v65, v80, v81
	v_cvt_pk_bf16_f32 v66, v76, v77
	v_cvt_pk_bf16_f32 v67, v78, v79
	global_store_dwordx4 v[74:75], v[64:67], off sc1
	s_nop 1
	v_cvt_pk_bf16_f32 v64, v68, v69
	v_cvt_pk_bf16_f32 v65, v70, v71
	v_cvt_pk_bf16_f32 v66, v72, v73
	v_cvt_pk_bf16_f32 v67, v84, v85
	global_store_dwordx4 v[74:75], v[64:67], off offset:256 sc1
	s_nop 1
	s_nop 0
	v_add_u32_e32 v65, 0x80, v128
	v_mad_i64_i32 v[66:67], s[4:5], v65, s0, v[132:133]
	v_lshl_add_u64 v[66:67], v[66:67], 0, v[134:135]
	s_nop 1
	v_mov_b32_e32 v64, v239
	v_pk_mul_f32 v[62:63], v[62:63], v[64:65] op_sel_hi:[1,0]
	v_pk_mul_f32 v[60:61], v[60:61], v[64:65] op_sel_hi:[1,0]
	v_pk_mul_f32 v[58:59], v[58:59], v[64:65] op_sel_hi:[1,0]
	v_pk_mul_f32 v[56:57], v[56:57], v[64:65] op_sel_hi:[1,0]
	v_pk_mul_f32 v[54:55], v[54:55], v[64:65] op_sel_hi:[1,0]
	v_pk_mul_f32 v[52:53], v[52:53], v[64:65] op_sel_hi:[1,0]
	v_pk_mul_f32 v[68:69], v[50:51], v[64:65] op_sel_hi:[1,0]
	v_pk_mul_f32 v[64:65], v[48:49], v[64:65] op_sel_hi:[1,0]
	v_cvt_pk_bf16_f32 v48, v60, v61
	v_cvt_pk_bf16_f32 v49, v62, v63
	v_cvt_pk_bf16_f32 v50, v56, v57
	v_cvt_pk_bf16_f32 v51, v58, v59
	global_store_dwordx4 v[66:67], v[48:51], off sc1
	s_nop 1
	v_cvt_pk_bf16_f32 v48, v52, v53
	v_cvt_pk_bf16_f32 v49, v54, v55
	v_cvt_pk_bf16_f32 v50, v64, v65
	v_cvt_pk_bf16_f32 v51, v68, v69
	global_store_dwordx4 v[66:67], v[48:51], off offset:256 sc1
	s_nop 1
	s_nop 0
	v_add_u32_e32 v49, 0x90, v128
	v_mad_i64_i32 v[50:51], s[4:5], v49, s0, v[132:133]
	v_lshl_add_u64 v[50:51], v[50:51], 0, v[134:135]
	s_nop 1
	v_mov_b32_e32 v48, v240
	v_pk_mul_f32 v[46:47], v[46:47], v[48:49] op_sel_hi:[1,0]
	v_pk_mul_f32 v[44:45], v[44:45], v[48:49] op_sel_hi:[1,0]
	v_pk_mul_f32 v[42:43], v[42:43], v[48:49] op_sel_hi:[1,0]
	v_pk_mul_f32 v[40:41], v[40:41], v[48:49] op_sel_hi:[1,0]
	v_pk_mul_f32 v[38:39], v[38:39], v[48:49] op_sel_hi:[1,0]
	v_pk_mul_f32 v[36:37], v[36:37], v[48:49] op_sel_hi:[1,0]
	v_pk_mul_f32 v[52:53], v[34:35], v[48:49] op_sel_hi:[1,0]
	v_pk_mul_f32 v[48:49], v[32:33], v[48:49] op_sel_hi:[1,0]
	v_cvt_pk_bf16_f32 v32, v44, v45
	v_cvt_pk_bf16_f32 v33, v46, v47
	v_cvt_pk_bf16_f32 v34, v40, v41
	v_cvt_pk_bf16_f32 v35, v42, v43
	global_store_dwordx4 v[50:51], v[32:35], off sc1
	s_nop 1
	v_cvt_pk_bf16_f32 v32, v36, v37
	v_cvt_pk_bf16_f32 v33, v38, v39
	v_cvt_pk_bf16_f32 v34, v48, v49
	v_cvt_pk_bf16_f32 v35, v52, v53
	global_store_dwordx4 v[50:51], v[32:35], off offset:256 sc1
	s_nop 1
	s_nop 0
	v_add_u32_e32 v33, 0xa0, v128
	v_mad_i64_i32 v[34:35], s[4:5], v33, s0, v[132:133]
	v_lshl_add_u64 v[34:35], v[34:35], 0, v[134:135]
	s_nop 1
	v_mov_b32_e32 v32, v241
	v_pk_mul_f32 v[30:31], v[30:31], v[32:33] op_sel_hi:[1,0]
	v_pk_mul_f32 v[28:29], v[28:29], v[32:33] op_sel_hi:[1,0]
	v_pk_mul_f32 v[26:27], v[26:27], v[32:33] op_sel_hi:[1,0]
	v_pk_mul_f32 v[24:25], v[24:25], v[32:33] op_sel_hi:[1,0]
	v_pk_mul_f32 v[22:23], v[22:23], v[32:33] op_sel_hi:[1,0]
	v_pk_mul_f32 v[20:21], v[20:21], v[32:33] op_sel_hi:[1,0]
	v_pk_mul_f32 v[36:37], v[18:19], v[32:33] op_sel_hi:[1,0]
	v_pk_mul_f32 v[32:33], v[16:17], v[32:33] op_sel_hi:[1,0]
	v_cvt_pk_bf16_f32 v16, v28, v29
	v_cvt_pk_bf16_f32 v17, v30, v31
	v_cvt_pk_bf16_f32 v18, v24, v25
	v_cvt_pk_bf16_f32 v19, v26, v27
	global_store_dwordx4 v[34:35], v[16:19], off sc1
	s_nop 1
	v_cvt_pk_bf16_f32 v16, v20, v21
	v_cvt_pk_bf16_f32 v17, v22, v23
	v_cvt_pk_bf16_f32 v18, v32, v33
	v_cvt_pk_bf16_f32 v19, v36, v37
	global_store_dwordx4 v[34:35], v[16:19], off offset:256 sc1
	s_nop 1
	s_nop 0
	v_add_u32_e32 v17, 0xb0, v128
	v_mad_i64_i32 v[18:19], s[0:1], v17, s0, v[132:133]
	v_lshl_add_u64 v[18:19], v[18:19], 0, v[134:135]
	v_readlane_b32 s0, v235, 41
	v_readlane_b32 s1, v235, 42
	s_and_b64 vcc, exec, s[0:1]
	s_nop 1
	v_mov_b32_e32 v16, v242
	v_pk_mul_f32 v[14:15], v[14:15], v[16:17] op_sel_hi:[1,0]
	v_pk_mul_f32 v[12:13], v[12:13], v[16:17] op_sel_hi:[1,0]
	v_pk_mul_f32 v[10:11], v[10:11], v[16:17] op_sel_hi:[1,0]
	v_pk_mul_f32 v[8:9], v[8:9], v[16:17] op_sel_hi:[1,0]
	v_pk_mul_f32 v[6:7], v[6:7], v[16:17] op_sel_hi:[1,0]
	v_pk_mul_f32 v[4:5], v[4:5], v[16:17] op_sel_hi:[1,0]
	v_pk_mul_f32 v[20:21], v[2:3], v[16:17] op_sel_hi:[1,0]
	v_pk_mul_f32 v[16:17], v[0:1], v[16:17] op_sel_hi:[1,0]
	v_cvt_pk_bf16_f32 v0, v12, v13
	v_cvt_pk_bf16_f32 v1, v14, v15
	v_cvt_pk_bf16_f32 v2, v8, v9
	v_cvt_pk_bf16_f32 v3, v10, v11
	global_store_dwordx4 v[18:19], v[0:3], off sc1
	s_nop 1
	v_cvt_pk_bf16_f32 v0, v4, v5
	v_cvt_pk_bf16_f32 v1, v6, v7
	v_cvt_pk_bf16_f32 v2, v16, v17
	v_cvt_pk_bf16_f32 v3, v20, v21
	global_store_dwordx4 v[18:19], v[0:3], off offset:256 sc1
	s_waitcnt vmcnt(0)
	s_barrier
	s_waitcnt vmcnt(0)
	s_barrier
	s_cbranch_vccnz .LBB0_228
	v_mbcnt_lo_u32_b32 v0, -1, 0
	v_mbcnt_hi_u32_b32 v0, -1, v0
	s_nop 0
	v_cmp_eq_u32_e32 vcc, 0, v0
	s_and_saveexec_b64 s[0:1], vcc
	s_cbranch_execz .LBB0_227
	s_mov_b64 s[6:7], exec
	s_nop 0
	s_waitcnt vmcnt(0)
	s_waitcnt vmcnt(0)
	v_mbcnt_lo_u32_b32 v0, s6, 0
	s_add_u32 s4, s78, 0x3700
	v_mbcnt_hi_u32_b32 v0, s7, v0
	s_addc_u32 s5, s79, 0
	v_cmp_eq_u32_e32 vcc, 0, v0
	s_and_saveexec_b64 s[8:9], vcc
	s_cbranch_execz .LBB0_217
	s_bcnt1_i32_b64 s6, s[6:7]
	v_mov_b32_e32 v0, 0
	v_mov_b32_e32 v1, s6
	global_atomic_add v0, v1, s[4:5]

.LBB0_922:
	v_ashrrev_i32_e32 v128, 1, v140
	v_and_b32_e32 v129, -8, v128
	v_lshl_add_u32 v128, s0, 8, v141
	s_lshl_b32 s0, s4, 8
	v_readlane_b32 s1, v235, 37
	s_or_b32 s0, s1, s0
	v_add_u32_e32 v132, s0, v129
	v_ashrrev_i32_e32 v133, 31, v132
	s_movk_i32 s0, 0x1040
	v_mov_b64_e32 v[130:131], s[52:53]
	v_ashrrev_i32_e32 v129, 31, v128
	v_mad_i64_i32 v[134:135], s[4:5], v128, s0, v[130:131]
	v_lshlrev_b64 v[132:133], 1, v[132:133]
	v_lshl_add_u64 v[136:137], v[134:135], 0, v[132:133]
	v_lshl_add_u64 v[134:135], v[128:129], 2, s[88:89]
	global_load_dword v138, v[134:135], off
	global_load_dword v236, v[134:135], off offset:64
	global_load_dword v237, v[134:135], off offset:128
	global_load_dword v238, v[134:135], off offset:192
	global_load_dword v239, v[134:135], off offset:512
	global_load_dword v240, v[134:135], off offset:576
	global_load_dword v241, v[134:135], off offset:640
	global_load_dword v242, v[134:135], off offset:704
	s_waitcnt vmcnt(0)
	v_pk_mul_f32 v[126:127], v[126:127], v[138:139] op_sel_hi:[1,0]
	v_pk_mul_f32 v[124:125], v[124:125], v[138:139] op_sel_hi:[1,0]
	v_pk_mul_f32 v[140:141], v[122:123], v[138:139] op_sel_hi:[1,0]
	v_pk_mul_f32 v[122:123], v[120:121], v[138:139] op_sel_hi:[1,0]
	v_cvt_pk_bf16_f32 v120, v124, v125
	v_cvt_pk_bf16_f32 v121, v126, v127
	v_pk_mul_f32 v[116:117], v[116:117], v[138:139] op_sel_hi:[1,0]
	v_cvt_pk_bf16_f32 v122, v122, v123
	v_cvt_pk_bf16_f32 v123, v140, v141
	global_store_dwordx4 v[136:137], v[120:123], off sc1
	v_pk_mul_f32 v[118:119], v[118:119], v[138:139] op_sel_hi:[1,0]
	s_nop 0
	v_pk_mul_f32 v[120:121], v[114:115], v[138:139] op_sel_hi:[1,0]
	v_pk_mul_f32 v[114:115], v[112:113], v[138:139] op_sel_hi:[1,0]
	v_cvt_pk_bf16_f32 v112, v116, v117
	v_cvt_pk_bf16_f32 v113, v118, v119
	s_nop 0
	v_cvt_pk_bf16_f32 v114, v114, v115
	v_cvt_pk_bf16_f32 v115, v120, v121
	global_store_dwordx4 v[136:137], v[112:115], off offset:256 sc1
	s_nop 1
	v_or_b32_e32 v112, 16, v128
	v_ashrrev_i32_e32 v113, 31, v112
	v_mad_i64_i32 v[114:115], s[4:5], v112, s0, v[130:131]
	v_lshl_add_u64 v[112:113], v[112:113], 2, s[88:89]
	s_nop 1
	v_lshl_add_u64 v[114:115], v[114:115], 0, v[132:133]
	s_nop 1
	v_mov_b32_e32 v112, v236
	v_pk_mul_f32 v[110:111], v[110:111], v[112:113] op_sel_hi:[1,0]
	v_pk_mul_f32 v[108:109], v[108:109], v[112:113] op_sel_hi:[1,0]
	v_pk_mul_f32 v[116:117], v[106:107], v[112:113] op_sel_hi:[1,0]
	v_pk_mul_f32 v[106:107], v[104:105], v[112:113] op_sel_hi:[1,0]
	v_cvt_pk_bf16_f32 v104, v108, v109
	v_cvt_pk_bf16_f32 v105, v110, v111
	v_pk_mul_f32 v[100:101], v[100:101], v[112:113] op_sel_hi:[1,0]
	v_cvt_pk_bf16_f32 v106, v106, v107
	v_cvt_pk_bf16_f32 v107, v116, v117
	global_store_dwordx4 v[114:115], v[104:107], off sc1
	v_pk_mul_f32 v[102:103], v[102:103], v[112:113] op_sel_hi:[1,0]
	s_nop 0
	v_pk_mul_f32 v[104:105], v[98:99], v[112:113] op_sel_hi:[1,0]
	v_pk_mul_f32 v[98:99], v[96:97], v[112:113] op_sel_hi:[1,0]
	v_cvt_pk_bf16_f32 v96, v100, v101
	v_cvt_pk_bf16_f32 v97, v102, v103
	s_nop 0
	v_cvt_pk_bf16_f32 v98, v98, v99
	v_cvt_pk_bf16_f32 v99, v104, v105
	global_store_dwordx4 v[114:115], v[96:99], off offset:256 sc1
	s_nop 1
	v_or_b32_e32 v96, 32, v128
	v_ashrrev_i32_e32 v97, 31, v96
	v_mad_i64_i32 v[98:99], s[4:5], v96, s0, v[130:131]
	v_lshl_add_u64 v[96:97], v[96:97], 2, s[88:89]
	s_nop 1
	v_lshl_add_u64 v[98:99], v[98:99], 0, v[132:133]
	s_nop 1
	v_mov_b32_e32 v96, v237
	v_pk_mul_f32 v[94:95], v[94:95], v[96:97] op_sel_hi:[1,0]
	v_pk_mul_f32 v[92:93], v[92:93], v[96:97] op_sel_hi:[1,0]
	v_pk_mul_f32 v[100:101], v[90:91], v[96:97] op_sel_hi:[1,0]
	v_pk_mul_f32 v[90:91], v[88:89], v[96:97] op_sel_hi:[1,0]
	v_cvt_pk_bf16_f32 v88, v92, v93
	v_cvt_pk_bf16_f32 v89, v94, v95
	v_pk_mul_f32 v[84:85], v[84:85], v[96:97] op_sel_hi:[1,0]
	v_cvt_pk_bf16_f32 v90, v90, v91
	v_cvt_pk_bf16_f32 v91, v100, v101
	global_store_dwordx4 v[98:99], v[88:91], off sc1
	v_pk_mul_f32 v[86:87], v[86:87], v[96:97] op_sel_hi:[1,0]
	s_nop 0
	v_pk_mul_f32 v[88:89], v[82:83], v[96:97] op_sel_hi:[1,0]
	v_pk_mul_f32 v[82:83], v[80:81], v[96:97] op_sel_hi:[1,0]
	v_cvt_pk_bf16_f32 v80, v84, v85
	v_cvt_pk_bf16_f32 v81, v86, v87
	s_nop 0
	v_cvt_pk_bf16_f32 v82, v82, v83
	v_cvt_pk_bf16_f32 v83, v88, v89
	global_store_dwordx4 v[98:99], v[80:83], off offset:256 sc1
	s_nop 1
	v_or_b32_e32 v80, 48, v128
	v_ashrrev_i32_e32 v81, 31, v80
	v_mad_i64_i32 v[82:83], s[4:5], v80, s0, v[130:131]
	v_lshl_add_u64 v[80:81], v[80:81], 2, s[88:89]
	s_nop 1
	v_lshl_add_u64 v[82:83], v[82:83], 0, v[132:133]
	s_nop 1
	v_mov_b32_e32 v80, v238
	v_pk_mul_f32 v[78:79], v[78:79], v[80:81] op_sel_hi:[1,0]
	v_pk_mul_f32 v[76:77], v[76:77], v[80:81] op_sel_hi:[1,0]
	v_pk_mul_f32 v[84:85], v[74:75], v[80:81] op_sel_hi:[1,0]
	v_pk_mul_f32 v[74:75], v[72:73], v[80:81] op_sel_hi:[1,0]
	v_cvt_pk_bf16_f32 v72, v76, v77
	v_cvt_pk_bf16_f32 v73, v78, v79
	v_pk_mul_f32 v[70:71], v[70:71], v[80:81] op_sel_hi:[1,0]
	v_cvt_pk_bf16_f32 v74, v74, v75
	v_cvt_pk_bf16_f32 v75, v84, v85
	global_store_dwordx4 v[82:83], v[72:75], off sc1
	v_pk_mul_f32 v[68:69], v[68:69], v[80:81] op_sel_hi:[1,0]
	s_nop 0
	v_pk_mul_f32 v[72:73], v[66:67], v[80:81] op_sel_hi:[1,0]
	v_pk_mul_f32 v[66:67], v[64:65], v[80:81] op_sel_hi:[1,0]
	v_cvt_pk_bf16_f32 v64, v68, v69
	v_cvt_pk_bf16_f32 v65, v70, v71
	s_nop 0
	v_cvt_pk_bf16_f32 v66, v66, v67
	v_cvt_pk_bf16_f32 v67, v72, v73
	global_store_dwordx4 v[82:83], v[64:67], off offset:256 sc1
	s_nop 1
	s_nop 1
	v_mov_b32_e32 v66, v239
	v_pk_mul_f32 v[62:63], v[62:63], v[66:67] op_sel_hi:[1,0]
	v_add_u32_e32 v64, 0x80, v128
	v_mad_i64_i32 v[64:65], s[4:5], v64, s0, v[130:131]
	v_lshl_add_u64 v[64:65], v[64:65], 0, v[132:133]
	v_pk_mul_f32 v[60:61], v[60:61], v[66:67] op_sel_hi:[1,0]
	v_pk_mul_f32 v[68:69], v[58:59], v[66:67] op_sel_hi:[1,0]
	v_pk_mul_f32 v[58:59], v[56:57], v[66:67] op_sel_hi:[1,0]
	v_cvt_pk_bf16_f32 v56, v60, v61
	v_cvt_pk_bf16_f32 v57, v62, v63
	v_pk_mul_f32 v[54:55], v[54:55], v[66:67] op_sel_hi:[1,0]
	v_cvt_pk_bf16_f32 v58, v58, v59
	v_cvt_pk_bf16_f32 v59, v68, v69
	global_store_dwordx4 v[64:65], v[56:59], off sc1
	v_pk_mul_f32 v[52:53], v[52:53], v[66:67] op_sel_hi:[1,0]
	s_nop 0
	v_pk_mul_f32 v[56:57], v[50:51], v[66:67] op_sel_hi:[1,0]
	v_pk_mul_f32 v[50:51], v[48:49], v[66:67] op_sel_hi:[1,0]
	v_cvt_pk_bf16_f32 v48, v52, v53
	v_cvt_pk_bf16_f32 v49, v54, v55
	s_nop 0
	v_cvt_pk_bf16_f32 v50, v50, v51
	v_cvt_pk_bf16_f32 v51, v56, v57
	global_store_dwordx4 v[64:65], v[48:51], off offset:256 sc1
	s_nop 1
	s_nop 1
	v_mov_b32_e32 v50, v240
	v_pk_mul_f32 v[46:47], v[46:47], v[50:51] op_sel_hi:[1,0]
	v_add_u32_e32 v48, 0x90, v128
	v_mad_i64_i32 v[48:49], s[4:5], v48, s0, v[130:131]
	v_lshl_add_u64 v[48:49], v[48:49], 0, v[132:133]
	v_pk_mul_f32 v[44:45], v[44:45], v[50:51] op_sel_hi:[1,0]
	v_pk_mul_f32 v[52:53], v[42:43], v[50:51] op_sel_hi:[1,0]
	v_pk_mul_f32 v[42:43], v[40:41], v[50:51] op_sel_hi:[1,0]
	v_cvt_pk_bf16_f32 v40, v44, v45
	v_cvt_pk_bf16_f32 v41, v46, v47
	v_pk_mul_f32 v[38:39], v[38:39], v[50:51] op_sel_hi:[1,0]
	v_cvt_pk_bf16_f32 v42, v42, v43
	v_cvt_pk_bf16_f32 v43, v52, v53
	global_store_dwordx4 v[48:49], v[40:43], off sc1
	v_pk_mul_f32 v[36:37], v[36:37], v[50:51] op_sel_hi:[1,0]
	s_nop 0
	v_pk_mul_f32 v[40:41], v[34:35], v[50:51] op_sel_hi:[1,0]
	v_pk_mul_f32 v[34:35], v[32:33], v[50:51] op_sel_hi:[1,0]
	v_cvt_pk_bf16_f32 v32, v36, v37
	v_cvt_pk_bf16_f32 v33, v38, v39
	s_nop 0
	v_cvt_pk_bf16_f32 v34, v34, v35
	v_cvt_pk_bf16_f32 v35, v40, v41
	global_store_dwordx4 v[48:49], v[32:35], off offset:256 sc1
	s_nop 1
	s_nop 1
	v_mov_b32_e32 v34, v241
	v_pk_mul_f32 v[30:31], v[30:31], v[34:35] op_sel_hi:[1,0]
	v_add_u32_e32 v32, 0xa0, v128
	v_mad_i64_i32 v[32:33], s[4:5], v32, s0, v[130:131]
	v_lshl_add_u64 v[32:33], v[32:33], 0, v[132:133]
	v_pk_mul_f32 v[28:29], v[28:29], v[34:35] op_sel_hi:[1,0]
	v_pk_mul_f32 v[36:37], v[26:27], v[34:35] op_sel_hi:[1,0]
	v_pk_mul_f32 v[26:27], v[24:25], v[34:35] op_sel_hi:[1,0]
	v_cvt_pk_bf16_f32 v24, v28, v29
	v_cvt_pk_bf16_f32 v25, v30, v31
	v_pk_mul_f32 v[22:23], v[22:23], v[34:35] op_sel_hi:[1,0]
	v_cvt_pk_bf16_f32 v26, v26, v27
	v_cvt_pk_bf16_f32 v27, v36, v37
	global_store_dwordx4 v[32:33], v[24:27], off sc1
	v_pk_mul_f32 v[20:21], v[20:21], v[34:35] op_sel_hi:[1,0]
	s_nop 0
	v_pk_mul_f32 v[24:25], v[18:19], v[34:35] op_sel_hi:[1,0]
	v_pk_mul_f32 v[18:19], v[16:17], v[34:35] op_sel_hi:[1,0]
	v_cvt_pk_bf16_f32 v16, v20, v21
	v_cvt_pk_bf16_f32 v17, v22, v23
	s_nop 0
	v_cvt_pk_bf16_f32 v18, v18, v19
	v_cvt_pk_bf16_f32 v19, v24, v25
	global_store_dwordx4 v[32:33], v[16:19], off offset:256 sc1
	s_nop 1
	s_nop 1
	v_mov_b32_e32 v18, v242
	v_pk_mul_f32 v[14:15], v[14:15], v[18:19] op_sel_hi:[1,0]
	v_add_u32_e32 v16, 0xb0, v128
	v_mad_i64_i32 v[16:17], s[0:1], v16, s0, v[130:131]
	v_lshl_add_u64 v[16:17], v[16:17], 0, v[132:133]
	v_pk_mul_f32 v[12:13], v[12:13], v[18:19] op_sel_hi:[1,0]
	v_pk_mul_f32 v[20:21], v[10:11], v[18:19] op_sel_hi:[1,0]
	v_pk_mul_f32 v[10:11], v[8:9], v[18:19] op_sel_hi:[1,0]
	v_cvt_pk_bf16_f32 v8, v12, v13
	v_cvt_pk_bf16_f32 v9, v14, v15
	v_pk_mul_f32 v[6:7], v[6:7], v[18:19] op_sel_hi:[1,0]
	v_cvt_pk_bf16_f32 v10, v10, v11
	v_cvt_pk_bf16_f32 v11, v20, v21
	global_store_dwordx4 v[16:17], v[8:11], off sc1
	v_pk_mul_f32 v[4:5], v[4:5], v[18:19] op_sel_hi:[1,0]
	v_readlane_b32 s0, v235, 41
	v_pk_mul_f32 v[8:9], v[2:3], v[18:19] op_sel_hi:[1,0]
	v_pk_mul_f32 v[2:3], v[0:1], v[18:19] op_sel_hi:[1,0]
	v_cvt_pk_bf16_f32 v0, v4, v5
	v_cvt_pk_bf16_f32 v1, v6, v7
	v_readlane_b32 s1, v235, 42
	v_cvt_pk_bf16_f32 v2, v2, v3
	v_cvt_pk_bf16_f32 v3, v8, v9
	global_store_dwordx4 v[16:17], v[0:3], off offset:256 sc1
	s_waitcnt vmcnt(0)
	s_barrier
	s_waitcnt vmcnt(0)
	s_and_b64 vcc, exec, s[0:1]
	s_barrier
	s_cbranch_vccnz .LBB0_936
	v_mbcnt_lo_u32_b32 v0, -1, 0
	v_mbcnt_hi_u32_b32 v0, -1, v0
	s_nop 0
	v_cmp_eq_u32_e32 vcc, 0, v0
	s_and_saveexec_b64 s[0:1], vcc
	s_cbranch_execz .LBB0_935
	s_mov_b64 s[6:7], exec
	s_nop 0
	s_waitcnt vmcnt(0)
	s_waitcnt vmcnt(0)
	v_mbcnt_lo_u32_b32 v0, s6, 0
	s_add_u32 s4, s78, 0x3800
	v_mbcnt_hi_u32_b32 v0, s7, v0
	s_addc_u32 s5, s79, 0
	v_cmp_eq_u32_e32 vcc, 0, v0
	s_and_saveexec_b64 s[8:9], vcc
	s_cbranch_execz .LBB0_926
	s_bcnt1_i32_b64 s6, s[6:7]
	v_mov_b32_e32 v0, 0
	v_mov_b32_e32 v1, s6
	global_atomic_add v0, v1, s[4:5]

.LBB0_1631:
	v_ashrrev_i32_e32 v128, 1, v140
	v_and_b32_e32 v129, -8, v128
	v_lshl_add_u32 v128, s0, 8, v141
	s_lshl_b32 s0, s4, 8
	v_readlane_b32 s1, v235, 37
	s_or_b32 s0, s1, s0
	v_add_u32_e32 v132, s0, v129
	v_ashrrev_i32_e32 v133, 31, v132
	s_movk_i32 s0, 0x1040
	v_mov_b64_e32 v[130:131], s[52:53]
	v_ashrrev_i32_e32 v129, 31, v128
	v_mad_i64_i32 v[134:135], s[4:5], v128, s0, v[130:131]
	v_lshlrev_b64 v[132:133], 1, v[132:133]
	v_lshl_add_u64 v[136:137], v[134:135], 0, v[132:133]
	v_lshl_add_u64 v[134:135], v[128:129], 2, s[88:89]
	global_load_dword v138, v[134:135], off
	global_load_dword v236, v[134:135], off offset:64
	global_load_dword v237, v[134:135], off offset:128
	global_load_dword v238, v[134:135], off offset:192
	global_load_dword v239, v[134:135], off offset:512
	global_load_dword v240, v[134:135], off offset:576
	global_load_dword v241, v[134:135], off offset:640
	global_load_dword v242, v[134:135], off offset:704
	s_waitcnt vmcnt(0)
	v_pk_mul_f32 v[126:127], v[126:127], v[138:139] op_sel_hi:[1,0]
	v_pk_mul_f32 v[124:125], v[124:125], v[138:139] op_sel_hi:[1,0]
	v_pk_mul_f32 v[140:141], v[122:123], v[138:139] op_sel_hi:[1,0]
	v_pk_mul_f32 v[122:123], v[120:121], v[138:139] op_sel_hi:[1,0]
	v_cvt_pk_bf16_f32 v120, v124, v125
	v_cvt_pk_bf16_f32 v121, v126, v127
	v_pk_mul_f32 v[116:117], v[116:117], v[138:139] op_sel_hi:[1,0]
	v_cvt_pk_bf16_f32 v122, v122, v123
	v_cvt_pk_bf16_f32 v123, v140, v141
	global_store_dwordx4 v[136:137], v[120:123], off sc1
	v_pk_mul_f32 v[118:119], v[118:119], v[138:139] op_sel_hi:[1,0]
	s_nop 0
	v_pk_mul_f32 v[120:121], v[114:115], v[138:139] op_sel_hi:[1,0]
	v_pk_mul_f32 v[114:115], v[112:113], v[138:139] op_sel_hi:[1,0]
	v_cvt_pk_bf16_f32 v112, v116, v117
	v_cvt_pk_bf16_f32 v113, v118, v119
	s_nop 0
	v_cvt_pk_bf16_f32 v114, v114, v115
	v_cvt_pk_bf16_f32 v115, v120, v121
	global_store_dwordx4 v[136:137], v[112:115], off offset:256 sc1
	s_nop 1
	v_or_b32_e32 v112, 16, v128
	v_ashrrev_i32_e32 v113, 31, v112
	v_mad_i64_i32 v[114:115], s[4:5], v112, s0, v[130:131]
	v_lshl_add_u64 v[112:113], v[112:113], 2, s[88:89]
	s_nop 1
	v_lshl_add_u64 v[114:115], v[114:115], 0, v[132:133]
	s_nop 1
	v_mov_b32_e32 v112, v236
	v_pk_mul_f32 v[110:111], v[110:111], v[112:113] op_sel_hi:[1,0]
	v_pk_mul_f32 v[108:109], v[108:109], v[112:113] op_sel_hi:[1,0]
	v_pk_mul_f32 v[116:117], v[106:107], v[112:113] op_sel_hi:[1,0]
	v_pk_mul_f32 v[106:107], v[104:105], v[112:113] op_sel_hi:[1,0]
	v_cvt_pk_bf16_f32 v104, v108, v109
	v_cvt_pk_bf16_f32 v105, v110, v111
	v_pk_mul_f32 v[100:101], v[100:101], v[112:113] op_sel_hi:[1,0]
	v_cvt_pk_bf16_f32 v106, v106, v107
	v_cvt_pk_bf16_f32 v107, v116, v117
	global_store_dwordx4 v[114:115], v[104:107], off sc1
	v_pk_mul_f32 v[102:103], v[102:103], v[112:113] op_sel_hi:[1,0]
	s_nop 0
	v_pk_mul_f32 v[104:105], v[98:99], v[112:113] op_sel_hi:[1,0]
	v_pk_mul_f32 v[98:99], v[96:97], v[112:113] op_sel_hi:[1,0]
	v_cvt_pk_bf16_f32 v96, v100, v101
	v_cvt_pk_bf16_f32 v97, v102, v103
	s_nop 0
	v_cvt_pk_bf16_f32 v98, v98, v99
	v_cvt_pk_bf16_f32 v99, v104, v105
	global_store_dwordx4 v[114:115], v[96:99], off offset:256 sc1
	s_nop 1
	v_or_b32_e32 v96, 32, v128
	v_ashrrev_i32_e32 v97, 31, v96
	v_mad_i64_i32 v[98:99], s[4:5], v96, s0, v[130:131]
	v_lshl_add_u64 v[96:97], v[96:97], 2, s[88:89]
	s_nop 1
	v_lshl_add_u64 v[98:99], v[98:99], 0, v[132:133]
	s_nop 1
	v_mov_b32_e32 v96, v237
	v_pk_mul_f32 v[94:95], v[94:95], v[96:97] op_sel_hi:[1,0]
	v_pk_mul_f32 v[92:93], v[92:93], v[96:97] op_sel_hi:[1,0]
	v_pk_mul_f32 v[100:101], v[90:91], v[96:97] op_sel_hi:[1,0]
	v_pk_mul_f32 v[90:91], v[88:89], v[96:97] op_sel_hi:[1,0]
	v_cvt_pk_bf16_f32 v88, v92, v93
	v_cvt_pk_bf16_f32 v89, v94, v95
	v_pk_mul_f32 v[84:85], v[84:85], v[96:97] op_sel_hi:[1,0]
	v_cvt_pk_bf16_f32 v90, v90, v91
	v_cvt_pk_bf16_f32 v91, v100, v101
	global_store_dwordx4 v[98:99], v[88:91], off sc1
	v_pk_mul_f32 v[86:87], v[86:87], v[96:97] op_sel_hi:[1,0]
	s_nop 0
	v_pk_mul_f32 v[88:89], v[82:83], v[96:97] op_sel_hi:[1,0]
	v_pk_mul_f32 v[82:83], v[80:81], v[96:97] op_sel_hi:[1,0]
	v_cvt_pk_bf16_f32 v80, v84, v85
	v_cvt_pk_bf16_f32 v81, v86, v87
	s_nop 0
	v_cvt_pk_bf16_f32 v82, v82, v83
	v_cvt_pk_bf16_f32 v83, v88, v89
	global_store_dwordx4 v[98:99], v[80:83], off offset:256 sc1
	s_nop 1
	v_or_b32_e32 v80, 48, v128
	v_ashrrev_i32_e32 v81, 31, v80
	v_mad_i64_i32 v[82:83], s[4:5], v80, s0, v[130:131]
	v_lshl_add_u64 v[80:81], v[80:81], 2, s[88:89]
	s_nop 1
	v_lshl_add_u64 v[82:83], v[82:83], 0, v[132:133]
	s_nop 1
	v_mov_b32_e32 v80, v238
	v_pk_mul_f32 v[78:79], v[78:79], v[80:81] op_sel_hi:[1,0]
	v_pk_mul_f32 v[76:77], v[76:77], v[80:81] op_sel_hi:[1,0]
	v_pk_mul_f32 v[84:85], v[74:75], v[80:81] op_sel_hi:[1,0]
	v_pk_mul_f32 v[74:75], v[72:73], v[80:81] op_sel_hi:[1,0]
	v_cvt_pk_bf16_f32 v72, v76, v77
	v_cvt_pk_bf16_f32 v73, v78, v79
	v_pk_mul_f32 v[70:71], v[70:71], v[80:81] op_sel_hi:[1,0]
	v_cvt_pk_bf16_f32 v74, v74, v75
	v_cvt_pk_bf16_f32 v75, v84, v85
	global_store_dwordx4 v[82:83], v[72:75], off sc1
	v_pk_mul_f32 v[68:69], v[68:69], v[80:81] op_sel_hi:[1,0]
	s_nop 0
	v_pk_mul_f32 v[72:73], v[66:67], v[80:81] op_sel_hi:[1,0]
	v_pk_mul_f32 v[66:67], v[64:65], v[80:81] op_sel_hi:[1,0]
	v_cvt_pk_bf16_f32 v64, v68, v69
	v_cvt_pk_bf16_f32 v65, v70, v71
	s_nop 0
	v_cvt_pk_bf16_f32 v66, v66, v67
	v_cvt_pk_bf16_f32 v67, v72, v73
	global_store_dwordx4 v[82:83], v[64:67], off offset:256 sc1
	s_nop 1
	s_nop 1
	v_mov_b32_e32 v66, v239
	v_pk_mul_f32 v[62:63], v[62:63], v[66:67] op_sel_hi:[1,0]
	v_add_u32_e32 v64, 0x80, v128
	v_mad_i64_i32 v[64:65], s[4:5], v64, s0, v[130:131]
	v_lshl_add_u64 v[64:65], v[64:65], 0, v[132:133]
	v_pk_mul_f32 v[60:61], v[60:61], v[66:67] op_sel_hi:[1,0]
	v_pk_mul_f32 v[68:69], v[58:59], v[66:67] op_sel_hi:[1,0]
	v_pk_mul_f32 v[58:59], v[56:57], v[66:67] op_sel_hi:[1,0]
	v_cvt_pk_bf16_f32 v56, v60, v61
	v_cvt_pk_bf16_f32 v57, v62, v63
	v_pk_mul_f32 v[54:55], v[54:55], v[66:67] op_sel_hi:[1,0]
	v_cvt_pk_bf16_f32 v58, v58, v59
	v_cvt_pk_bf16_f32 v59, v68, v69
	global_store_dwordx4 v[64:65], v[56:59], off sc1
	v_pk_mul_f32 v[52:53], v[52:53], v[66:67] op_sel_hi:[1,0]
	s_nop 0
	v_pk_mul_f32 v[56:57], v[50:51], v[66:67] op_sel_hi:[1,0]
	v_pk_mul_f32 v[50:51], v[48:49], v[66:67] op_sel_hi:[1,0]
	v_cvt_pk_bf16_f32 v48, v52, v53
	v_cvt_pk_bf16_f32 v49, v54, v55
	s_nop 0
	v_cvt_pk_bf16_f32 v50, v50, v51
	v_cvt_pk_bf16_f32 v51, v56, v57
	global_store_dwordx4 v[64:65], v[48:51], off offset:256 sc1
	s_nop 1
	s_nop 1
	v_mov_b32_e32 v50, v240
	v_pk_mul_f32 v[46:47], v[46:47], v[50:51] op_sel_hi:[1,0]
	v_add_u32_e32 v48, 0x90, v128
	v_mad_i64_i32 v[48:49], s[4:5], v48, s0, v[130:131]
	v_lshl_add_u64 v[48:49], v[48:49], 0, v[132:133]
	v_pk_mul_f32 v[44:45], v[44:45], v[50:51] op_sel_hi:[1,0]
	v_pk_mul_f32 v[52:53], v[42:43], v[50:51] op_sel_hi:[1,0]
	v_pk_mul_f32 v[42:43], v[40:41], v[50:51] op_sel_hi:[1,0]
	v_cvt_pk_bf16_f32 v40, v44, v45
	v_cvt_pk_bf16_f32 v41, v46, v47
	v_pk_mul_f32 v[38:39], v[38:39], v[50:51] op_sel_hi:[1,0]
	v_cvt_pk_bf16_f32 v42, v42, v43
	v_cvt_pk_bf16_f32 v43, v52, v53
	global_store_dwordx4 v[48:49], v[40:43], off sc1
	v_pk_mul_f32 v[36:37], v[36:37], v[50:51] op_sel_hi:[1,0]
	s_nop 0
	v_pk_mul_f32 v[40:41], v[34:35], v[50:51] op_sel_hi:[1,0]
	v_pk_mul_f32 v[34:35], v[32:33], v[50:51] op_sel_hi:[1,0]
	v_cvt_pk_bf16_f32 v32, v36, v37
	v_cvt_pk_bf16_f32 v33, v38, v39
	s_nop 0
	v_cvt_pk_bf16_f32 v34, v34, v35
	v_cvt_pk_bf16_f32 v35, v40, v41
	global_store_dwordx4 v[48:49], v[32:35], off offset:256 sc1
	s_nop 1
	s_nop 1
	v_mov_b32_e32 v34, v241
	v_pk_mul_f32 v[30:31], v[30:31], v[34:35] op_sel_hi:[1,0]
	v_add_u32_e32 v32, 0xa0, v128
	v_mad_i64_i32 v[32:33], s[4:5], v32, s0, v[130:131]
	v_lshl_add_u64 v[32:33], v[32:33], 0, v[132:133]
	v_pk_mul_f32 v[28:29], v[28:29], v[34:35] op_sel_hi:[1,0]
	v_pk_mul_f32 v[36:37], v[26:27], v[34:35] op_sel_hi:[1,0]
	v_pk_mul_f32 v[26:27], v[24:25], v[34:35] op_sel_hi:[1,0]
	v_cvt_pk_bf16_f32 v24, v28, v29
	v_cvt_pk_bf16_f32 v25, v30, v31
	v_pk_mul_f32 v[22:23], v[22:23], v[34:35] op_sel_hi:[1,0]
	v_cvt_pk_bf16_f32 v26, v26, v27
	v_cvt_pk_bf16_f32 v27, v36, v37
	global_store_dwordx4 v[32:33], v[24:27], off sc1
	v_pk_mul_f32 v[20:21], v[20:21], v[34:35] op_sel_hi:[1,0]
	s_nop 0
	v_pk_mul_f32 v[24:25], v[18:19], v[34:35] op_sel_hi:[1,0]
	v_pk_mul_f32 v[18:19], v[16:17], v[34:35] op_sel_hi:[1,0]
	v_cvt_pk_bf16_f32 v16, v20, v21
	v_cvt_pk_bf16_f32 v17, v22, v23
	s_nop 0
	v_cvt_pk_bf16_f32 v18, v18, v19
	v_cvt_pk_bf16_f32 v19, v24, v25
	global_store_dwordx4 v[32:33], v[16:19], off offset:256 sc1
	s_nop 1
	s_nop 1
	v_mov_b32_e32 v18, v242
	v_pk_mul_f32 v[14:15], v[14:15], v[18:19] op_sel_hi:[1,0]
	v_add_u32_e32 v16, 0xb0, v128
	v_mad_i64_i32 v[16:17], s[0:1], v16, s0, v[130:131]
	v_lshl_add_u64 v[16:17], v[16:17], 0, v[132:133]
	v_pk_mul_f32 v[12:13], v[12:13], v[18:19] op_sel_hi:[1,0]
	v_pk_mul_f32 v[20:21], v[10:11], v[18:19] op_sel_hi:[1,0]
	v_pk_mul_f32 v[10:11], v[8:9], v[18:19] op_sel_hi:[1,0]
	v_cvt_pk_bf16_f32 v8, v12, v13
	v_cvt_pk_bf16_f32 v9, v14, v15
	v_pk_mul_f32 v[6:7], v[6:7], v[18:19] op_sel_hi:[1,0]
	v_cvt_pk_bf16_f32 v10, v10, v11
	v_cvt_pk_bf16_f32 v11, v20, v21
	global_store_dwordx4 v[16:17], v[8:11], off sc1
	v_pk_mul_f32 v[4:5], v[4:5], v[18:19] op_sel_hi:[1,0]
	v_readlane_b32 s0, v235, 41
	v_pk_mul_f32 v[8:9], v[2:3], v[18:19] op_sel_hi:[1,0]
	v_pk_mul_f32 v[2:3], v[0:1], v[18:19] op_sel_hi:[1,0]
	v_cvt_pk_bf16_f32 v0, v4, v5
	v_cvt_pk_bf16_f32 v1, v6, v7
	v_readlane_b32 s1, v235, 42
	v_cvt_pk_bf16_f32 v2, v2, v3
	v_cvt_pk_bf16_f32 v3, v8, v9
	global_store_dwordx4 v[16:17], v[0:3], off offset:256 sc1
	s_waitcnt vmcnt(0)
	s_barrier
	s_waitcnt vmcnt(0)
	s_and_b64 vcc, exec, s[0:1]
	s_barrier
	s_cbranch_vccnz .LBB0_1645
	v_mbcnt_lo_u32_b32 v0, -1, 0
	v_mbcnt_hi_u32_b32 v0, -1, v0
	s_nop 0
	v_cmp_eq_u32_e32 vcc, 0, v0
	s_and_saveexec_b64 s[0:1], vcc
	s_cbranch_execz .LBB0_1644
	s_mov_b64 s[6:7], exec
	s_nop 0
	s_waitcnt vmcnt(0)
	s_waitcnt vmcnt(0)
	v_mbcnt_lo_u32_b32 v0, s6, 0
	s_add_u32 s4, s78, 0x3900
	v_mbcnt_hi_u32_b32 v0, s7, v0
	s_addc_u32 s5, s79, 0
	v_cmp_eq_u32_e32 vcc, 0, v0
	s_and_saveexec_b64 s[8:9], vcc
	s_cbranch_execz .LBB0_1635
	s_bcnt1_i32_b64 s6, s[6:7]
	v_mov_b32_e32 v0, 0
	v_mov_b32_e32 v1, s6
	global_atomic_add v0, v1, s[4:5]

.LBB0_2340:
	v_lshl_add_u32 v128, s4, 8, v141
	v_ashrrev_i32_e32 v129, 31, v128
	v_lshl_add_u64 v[130:131], v[128:129], 2, s[88:89]
	global_load_dword v136, v[130:131], off
	global_load_dword v236, v[130:131], off offset:64
	global_load_dword v237, v[130:131], off offset:128
	global_load_dword v238, v[130:131], off offset:192
	global_load_dword v239, v[130:131], off offset:512
	global_load_dword v240, v[130:131], off offset:576
	global_load_dword v241, v[130:131], off offset:640
	global_load_dword v242, v[130:131], off offset:704
	v_ashrrev_i32_e32 v129, 1, v140
	s_lshl_b32 s1, s0, 8
	v_readlane_b32 s4, v235, 37
	v_and_b32_e32 v129, -8, v129
	s_or_b32 s1, s4, s1
	v_add_u32_e32 v134, s1, v129
	s_movk_i32 s0, 0x1040
	v_mov_b64_e32 v[132:133], s[52:53]
	v_ashrrev_i32_e32 v135, 31, v134
	v_mad_i64_i32 v[138:139], s[4:5], v128, s0, v[132:133]
	v_or_b32_e32 v140, 16, v128
	v_lshlrev_b64 v[134:135], 1, v[134:135]
	v_ashrrev_i32_e32 v141, 31, v140
	v_lshl_add_u64 v[138:139], v[138:139], 0, v[134:135]
	v_lshl_add_u64 v[142:143], v[140:141], 2, s[88:89]
	s_waitcnt vmcnt(0)
	v_pk_mul_f32 v[126:127], v[126:127], v[136:137] op_sel_hi:[1,0]
	v_pk_mul_f32 v[124:125], v[124:125], v[136:137] op_sel_hi:[1,0]
	v_pk_mul_f32 v[122:123], v[122:123], v[136:137] op_sel_hi:[1,0]
	v_pk_mul_f32 v[120:121], v[120:121], v[136:137] op_sel_hi:[1,0]
	v_pk_mul_f32 v[118:119], v[118:119], v[136:137] op_sel_hi:[1,0]
	v_pk_mul_f32 v[116:117], v[116:117], v[136:137] op_sel_hi:[1,0]
	v_pk_mul_f32 v[144:145], v[114:115], v[136:137] op_sel_hi:[1,0]
	v_pk_mul_f32 v[136:137], v[112:113], v[136:137] op_sel_hi:[1,0]
	v_cvt_pk_bf16_f32 v112, v124, v125
	v_cvt_pk_bf16_f32 v113, v126, v127
	v_cvt_pk_bf16_f32 v114, v120, v121
	v_cvt_pk_bf16_f32 v115, v122, v123
	global_store_dwordx4 v[138:139], v[112:115], off sc1
	s_nop 1
	v_cvt_pk_bf16_f32 v112, v116, v117
	v_cvt_pk_bf16_f32 v113, v118, v119
	v_cvt_pk_bf16_f32 v114, v136, v137
	v_cvt_pk_bf16_f32 v115, v144, v145
	global_store_dwordx4 v[138:139], v[112:115], off offset:256 sc1
	s_nop 1
	v_mad_i64_i32 v[116:117], s[4:5], v140, s0, v[132:133]
	v_or_b32_e32 v114, 32, v128
	v_ashrrev_i32_e32 v115, 31, v114
	v_lshl_add_u64 v[116:117], v[116:117], 0, v[134:135]
	v_lshl_add_u64 v[118:119], v[114:115], 2, s[88:89]
	s_nop 1
	v_mov_b32_e32 v112, v236
	v_pk_mul_f32 v[110:111], v[110:111], v[112:113] op_sel_hi:[1,0]
	v_pk_mul_f32 v[108:109], v[108:109], v[112:113] op_sel_hi:[1,0]
	v_pk_mul_f32 v[106:107], v[106:107], v[112:113] op_sel_hi:[1,0]
	v_pk_mul_f32 v[104:105], v[104:105], v[112:113] op_sel_hi:[1,0]
	v_pk_mul_f32 v[102:103], v[102:103], v[112:113] op_sel_hi:[1,0]
	v_pk_mul_f32 v[100:101], v[100:101], v[112:113] op_sel_hi:[1,0]
	v_pk_mul_f32 v[120:121], v[98:99], v[112:113] op_sel_hi:[1,0]
	v_pk_mul_f32 v[112:113], v[96:97], v[112:113] op_sel_hi:[1,0]
	v_cvt_pk_bf16_f32 v96, v108, v109
	v_cvt_pk_bf16_f32 v97, v110, v111
	v_cvt_pk_bf16_f32 v98, v104, v105
	v_cvt_pk_bf16_f32 v99, v106, v107
	global_store_dwordx4 v[116:117], v[96:99], off sc1
	s_nop 1
	v_cvt_pk_bf16_f32 v96, v100, v101
	v_cvt_pk_bf16_f32 v97, v102, v103
	v_cvt_pk_bf16_f32 v98, v112, v113
	v_cvt_pk_bf16_f32 v99, v120, v121
	global_store_dwordx4 v[116:117], v[96:99], off offset:256 sc1
	s_nop 1
	v_mad_i64_i32 v[100:101], s[4:5], v114, s0, v[132:133]
	v_or_b32_e32 v98, 48, v128
	v_ashrrev_i32_e32 v99, 31, v98
	v_lshl_add_u64 v[100:101], v[100:101], 0, v[134:135]
	v_lshl_add_u64 v[102:103], v[98:99], 2, s[88:89]
	s_nop 1
	v_mov_b32_e32 v96, v237
	v_pk_mul_f32 v[94:95], v[94:95], v[96:97] op_sel_hi:[1,0]
	v_pk_mul_f32 v[92:93], v[92:93], v[96:97] op_sel_hi:[1,0]
	v_pk_mul_f32 v[90:91], v[90:91], v[96:97] op_sel_hi:[1,0]
	v_pk_mul_f32 v[88:89], v[88:89], v[96:97] op_sel_hi:[1,0]
	v_pk_mul_f32 v[82:83], v[82:83], v[96:97] op_sel_hi:[1,0]
	v_pk_mul_f32 v[80:81], v[80:81], v[96:97] op_sel_hi:[1,0]
	v_pk_mul_f32 v[104:105], v[74:75], v[96:97] op_sel_hi:[1,0]
	v_pk_mul_f32 v[96:97], v[72:73], v[96:97] op_sel_hi:[1,0]
	v_cvt_pk_bf16_f32 v72, v92, v93
	v_cvt_pk_bf16_f32 v73, v94, v95
	v_cvt_pk_bf16_f32 v74, v88, v89
	v_cvt_pk_bf16_f32 v75, v90, v91
	global_store_dwordx4 v[100:101], v[72:75], off sc1
	s_nop 1
	v_cvt_pk_bf16_f32 v72, v80, v81
	v_cvt_pk_bf16_f32 v73, v82, v83
	v_cvt_pk_bf16_f32 v74, v96, v97
	v_cvt_pk_bf16_f32 v75, v104, v105
	global_store_dwordx4 v[100:101], v[72:75], off offset:256 sc1
	s_nop 1
	s_nop 1
	v_mov_b32_e32 v72, v238
	v_pk_mul_f32 v[80:81], v[86:87], v[72:73] op_sel_hi:[1,0]
	v_mad_i64_i32 v[74:75], s[4:5], v98, s0, v[132:133]
	v_lshl_add_u64 v[74:75], v[74:75], 0, v[134:135]
	v_pk_mul_f32 v[82:83], v[84:85], v[72:73] op_sel_hi:[1,0]
	v_pk_mul_f32 v[78:79], v[78:79], v[72:73] op_sel_hi:[1,0]
	v_pk_mul_f32 v[76:77], v[76:77], v[72:73] op_sel_hi:[1,0]
	v_pk_mul_f32 v[70:71], v[70:71], v[72:73] op_sel_hi:[1,0]
	v_pk_mul_f32 v[68:69], v[68:69], v[72:73] op_sel_hi:[1,0]
	v_pk_mul_f32 v[84:85], v[66:67], v[72:73] op_sel_hi:[1,0]
	v_pk_mul_f32 v[72:73], v[64:65], v[72:73] op_sel_hi:[1,0]
	v_cvt_pk_bf16_f32 v64, v82, v83
	v_cvt_pk_bf16_f32 v65, v80, v81
	v_cvt_pk_bf16_f32 v66, v76, v77
	v_cvt_pk_bf16_f32 v67, v78, v79
	global_store_dwordx4 v[74:75], v[64:67], off sc1
	s_nop 1
	v_cvt_pk_bf16_f32 v64, v68, v69
	v_cvt_pk_bf16_f32 v65, v70, v71
	v_cvt_pk_bf16_f32 v66, v72, v73
	v_cvt_pk_bf16_f32 v67, v84, v85
	global_store_dwordx4 v[74:75], v[64:67], off offset:256 sc1
	s_nop 1
	s_nop 0
	v_add_u32_e32 v65, 0x80, v128
	v_mad_i64_i32 v[66:67], s[4:5], v65, s0, v[132:133]
	v_lshl_add_u64 v[66:67], v[66:67], 0, v[134:135]
	s_nop 1
	v_mov_b32_e32 v64, v239
	v_pk_mul_f32 v[62:63], v[62:63], v[64:65] op_sel_hi:[1,0]
	v_pk_mul_f32 v[60:61], v[60:61], v[64:65] op_sel_hi:[1,0]
	v_pk_mul_f32 v[58:59], v[58:59], v[64:65] op_sel_hi:[1,0]
	v_pk_mul_f32 v[56:57], v[56:57], v[64:65] op_sel_hi:[1,0]
	v_pk_mul_f32 v[54:55], v[54:55], v[64:65] op_sel_hi:[1,0]
	v_pk_mul_f32 v[52:53], v[52:53], v[64:65] op_sel_hi:[1,0]
	v_pk_mul_f32 v[68:69], v[50:51], v[64:65] op_sel_hi:[1,0]
	v_pk_mul_f32 v[64:65], v[48:49], v[64:65] op_sel_hi:[1,0]
	v_cvt_pk_bf16_f32 v48, v60, v61
	v_cvt_pk_bf16_f32 v49, v62, v63
	v_cvt_pk_bf16_f32 v50, v56, v57
	v_cvt_pk_bf16_f32 v51, v58, v59
	global_store_dwordx4 v[66:67], v[48:51], off sc1
	s_nop 1
	v_cvt_pk_bf16_f32 v48, v52, v53
	v_cvt_pk_bf16_f32 v49, v54, v55
	v_cvt_pk_bf16_f32 v50, v64, v65
	v_cvt_pk_bf16_f32 v51, v68, v69
	global_store_dwordx4 v[66:67], v[48:51], off offset:256 sc1
	s_nop 1
	s_nop 0
	v_add_u32_e32 v49, 0x90, v128
	v_mad_i64_i32 v[50:51], s[4:5], v49, s0, v[132:133]
	v_lshl_add_u64 v[50:51], v[50:51], 0, v[134:135]
	s_nop 1
	v_mov_b32_e32 v48, v240
	v_pk_mul_f32 v[46:47], v[46:47], v[48:49] op_sel_hi:[1,0]
	v_pk_mul_f32 v[44:45], v[44:45], v[48:49] op_sel_hi:[1,0]
	v_pk_mul_f32 v[42:43], v[42:43], v[48:49] op_sel_hi:[1,0]
	v_pk_mul_f32 v[40:41], v[40:41], v[48:49] op_sel_hi:[1,0]
	v_pk_mul_f32 v[38:39], v[38:39], v[48:49] op_sel_hi:[1,0]
	v_pk_mul_f32 v[36:37], v[36:37], v[48:49] op_sel_hi:[1,0]
	v_pk_mul_f32 v[52:53], v[34:35], v[48:49] op_sel_hi:[1,0]
	v_pk_mul_f32 v[48:49], v[32:33], v[48:49] op_sel_hi:[1,0]
	v_cvt_pk_bf16_f32 v32, v44, v45
	v_cvt_pk_bf16_f32 v33, v46, v47
	v_cvt_pk_bf16_f32 v34, v40, v41
	v_cvt_pk_bf16_f32 v35, v42, v43
	global_store_dwordx4 v[50:51], v[32:35], off sc1
	s_nop 1
	v_cvt_pk_bf16_f32 v32, v36, v37
	v_cvt_pk_bf16_f32 v33, v38, v39
	v_cvt_pk_bf16_f32 v34, v48, v49
	v_cvt_pk_bf16_f32 v35, v52, v53
	global_store_dwordx4 v[50:51], v[32:35], off offset:256 sc1
	s_nop 1
	s_nop 0
	v_add_u32_e32 v33, 0xa0, v128
	v_mad_i64_i32 v[34:35], s[4:5], v33, s0, v[132:133]
	v_lshl_add_u64 v[34:35], v[34:35], 0, v[134:135]
	s_nop 1
	v_mov_b32_e32 v32, v241
	v_pk_mul_f32 v[30:31], v[30:31], v[32:33] op_sel_hi:[1,0]
	v_pk_mul_f32 v[28:29], v[28:29], v[32:33] op_sel_hi:[1,0]
	v_pk_mul_f32 v[26:27], v[26:27], v[32:33] op_sel_hi:[1,0]
	v_pk_mul_f32 v[24:25], v[24:25], v[32:33] op_sel_hi:[1,0]
	v_pk_mul_f32 v[22:23], v[22:23], v[32:33] op_sel_hi:[1,0]
	v_pk_mul_f32 v[20:21], v[20:21], v[32:33] op_sel_hi:[1,0]
	v_pk_mul_f32 v[36:37], v[18:19], v[32:33] op_sel_hi:[1,0]
	v_pk_mul_f32 v[32:33], v[16:17], v[32:33] op_sel_hi:[1,0]
	v_cvt_pk_bf16_f32 v16, v28, v29
	v_cvt_pk_bf16_f32 v17, v30, v31
	v_cvt_pk_bf16_f32 v18, v24, v25
	v_cvt_pk_bf16_f32 v19, v26, v27
	global_store_dwordx4 v[34:35], v[16:19], off sc1
	s_nop 1
	v_cvt_pk_bf16_f32 v16, v20, v21
	v_cvt_pk_bf16_f32 v17, v22, v23
	v_cvt_pk_bf16_f32 v18, v32, v33
	v_cvt_pk_bf16_f32 v19, v36, v37
	global_store_dwordx4 v[34:35], v[16:19], off offset:256 sc1
	s_nop 1
	s_nop 0
	v_add_u32_e32 v17, 0xb0, v128
	v_mad_i64_i32 v[18:19], s[0:1], v17, s0, v[132:133]
	v_lshl_add_u64 v[18:19], v[18:19], 0, v[134:135]
	v_readlane_b32 s0, v235, 41
	v_readlane_b32 s1, v235, 42
	s_and_b64 vcc, exec, s[0:1]
	s_nop 1
	v_mov_b32_e32 v16, v242
	v_pk_mul_f32 v[14:15], v[14:15], v[16:17] op_sel_hi:[1,0]
	v_pk_mul_f32 v[12:13], v[12:13], v[16:17] op_sel_hi:[1,0]
	v_pk_mul_f32 v[10:11], v[10:11], v[16:17] op_sel_hi:[1,0]
	v_pk_mul_f32 v[8:9], v[8:9], v[16:17] op_sel_hi:[1,0]
	v_pk_mul_f32 v[6:7], v[6:7], v[16:17] op_sel_hi:[1,0]
	v_pk_mul_f32 v[4:5], v[4:5], v[16:17] op_sel_hi:[1,0]
	v_pk_mul_f32 v[20:21], v[2:3], v[16:17] op_sel_hi:[1,0]
	v_pk_mul_f32 v[16:17], v[0:1], v[16:17] op_sel_hi:[1,0]
	v_cvt_pk_bf16_f32 v0, v12, v13
	v_cvt_pk_bf16_f32 v1, v14, v15
	v_cvt_pk_bf16_f32 v2, v8, v9
	v_cvt_pk_bf16_f32 v3, v10, v11
	global_store_dwordx4 v[18:19], v[0:3], off sc1
	s_nop 1
	v_cvt_pk_bf16_f32 v0, v4, v5
	v_cvt_pk_bf16_f32 v1, v6, v7
	v_cvt_pk_bf16_f32 v2, v16, v17
	v_cvt_pk_bf16_f32 v3, v20, v21
	global_store_dwordx4 v[18:19], v[0:3], off offset:256 sc1
	s_waitcnt vmcnt(0)
	s_barrier
	s_waitcnt vmcnt(0)
	s_barrier
	s_cbranch_vccnz .LBB0_2354
	v_mbcnt_lo_u32_b32 v0, -1, 0
	v_mbcnt_hi_u32_b32 v0, -1, v0
	s_nop 0
	v_cmp_eq_u32_e32 vcc, 0, v0
	s_and_saveexec_b64 s[0:1], vcc
	s_cbranch_execz .LBB0_2353
	s_mov_b64 s[6:7], exec
	s_nop 0
	s_waitcnt vmcnt(0)
	s_waitcnt vmcnt(0)
	v_mbcnt_lo_u32_b32 v0, s6, 0
	s_add_u32 s4, s78, 0x3a00
	v_mbcnt_hi_u32_b32 v0, s7, v0
	s_addc_u32 s5, s79, 0
	v_cmp_eq_u32_e32 vcc, 0, v0
	s_and_saveexec_b64 s[8:9], vcc
	s_cbranch_execz .LBB0_2344
	s_bcnt1_i32_b64 s6, s[6:7]
	v_mov_b32_e32 v0, 0
	v_mov_b32_e32 v1, s6
	global_atomic_add v0, v1, s[4:5]
